# conv unit loop: row-load waits counted (vmcnt 4: only the previous unit's 4 output stores trail them), entry drain in the preheader
# speedup vs baseline: 1.0277x; 1.0040x over previous
; #define LAS __attribute__((address_space(3)))
; #define CONV_LOAD(uu) do { const int b_ = (uu) >> 8, t0_ = ((uu) & 255) * 32; _Pragma("unroll") for (int i = 0; i < 8; ++i) { const int idx = tid + i * 512, row = idx >> 6, c16 = idx & 63, tok = t0_ - 15 + row; \
;         pf[i] = (v4u){0u, 0u, 0u, 0u}; if (idx < 62 * 64 && tok >= 0 && tok < SEQ) pf[i] = *(const v4u*)(CG + ((size_t)(b_ * SEQ + tok) * CW + c16 * 8)); } } while (0)
; __device__ __forceinline__ void conv_phase(const Frame& F, const bf16* CG, bf16* CAT, const float* dw_w, const float* dw_b, const float* ln_g, const float* ln_b) {
;     ...
;     const int tid = tid_, cp = tid & 255, th = tid >> 8, lane = tid & 63, wave = tid >> 6;
;     f32x2 w[KC];
; #pragma unroll
;     for (int j = 0; j < KC; ++j) w[j] = *(const f32x2*)(dw_w + j * CW + 2 * cp);
;     const f32x2 bias = *(const f32x2*)(dw_b + 2 * cp);
;     f32x4 lg[2], lb[2];
; #pragma unroll
;     for (int j = 0; j < 2; ++j) { lg[j] = *(const f32x4*)(ln_g + 8 * lane + 4 * j); lb[j] = *(const f32x4*)(ln_b + 8 * lane + 4 * j); }
;     v4u pf[8];
;     ...
;     const int ub = (F.vcu >> 5) * 256 + (F.vcu & 31);
;     CONV_LOAD(ub);
;     for (int kk = 0; kk < 8; ++kk) { const int u = ub + 32 * kk;
;         const int b = u >> 8, t0 = (u & 255) * 32;
; #pragma unroll
;         for (int i = 0; i < 8; ++i) { const int idx = tid + i * 512; if (idx < 62 * 64) *(LAS v4u*)(it + idx * 4) = pf[i]; }
;     ...
;             for (int o_ = 1; o_ < 64; o_ <<= 1) {
;                 float t1[4], t2[4];
; #pragma unroll
;                 for (int q = 0; q < 4; ++q) { t1[q] = __shfl_xor(s1[q], o_); t2[q] = __shfl_xor(s2[q], o_); }
.LBB0_281:
	s_or_b64 exec, exec, s[18:19]
	v_lshlrev_b32_e32 v3, 3, v53
	v_ashrrev_i32_e32 v53, 8, v52
	v_mov_b32_e32 v63, 2
	v_lshlrev_b32_sdwa v2, v248, v52 dst_sel:DWORD dst_unused:UNUSED_PAD src0_sel:DWORD src1_sel:BYTE_0
	v_lshlrev_b32_e32 v62, 14, v53
	v_lshlrev_b32_sdwa v52, v63, v52 dst_sel:DWORD dst_unused:UNUSED_PAD src0_sel:DWORD src1_sel:BYTE_0
	v_add3_u32 v190, 0, v62, v52
	v_lshl_add_u32 v52, v53, 15, 0
	v_lshlrev_b32_e32 v2, 2, v2
	s_mov_b32 s18, 0xf800
	v_add3_u32 v191, v52, v2, s18
	v_lshlrev_b32_e32 v2, 13, v182
	v_add3_u32 v192, 0, v2, v55
	v_and_b32_e32 v2, 64, v249
	v_add_u32_e32 v52, 64, v2
	v_lshlrev_b32_e32 v53, 4, v58
	v_xor_b32_e32 v58, 1, v249
	v_cmp_lt_i32_e64 s[18:19], v58, v52
	v_lshlrev_b32_e32 v2, 1, v3
	v_mov_b32_e32 v3, v0
	v_cndmask_b32_e64 v58, v249, v58, s[18:19]
	v_lshlrev_b32_e32 v195, 2, v58
	v_xor_b32_e32 v58, 2, v249
	v_cmp_lt_i32_e64 s[18:19], v58, v52
	v_lshl_add_u64 v[150:151], s[50:51], 0, v[2:3]
	v_lshlrev_b32_e32 v2, 4, v56
	v_cndmask_b32_e64 v58, v249, v58, s[18:19]
	v_lshlrev_b32_e32 v196, 2, v58
	v_xor_b32_e32 v58, 4, v249
	v_cmp_lt_i32_e64 s[18:19], v58, v52
	v_lshlrev_b32_e32 v3, 4, v57
	v_lshlrev_b32_e32 v55, 4, v59
	v_cndmask_b32_e64 v58, v249, v58, s[18:19]
	v_lshlrev_b32_e32 v197, 2, v58
	v_xor_b32_e32 v58, 8, v249
	v_cmp_lt_i32_e64 s[18:19], v58, v52
	v_lshlrev_b32_e32 v56, 4, v60
	v_lshlrev_b32_e32 v57, 4, v61
	v_cndmask_b32_e64 v58, v249, v58, s[18:19]
	v_lshlrev_b32_e32 v198, 2, v58
	v_xor_b32_e32 v58, 16, v249
	v_cmp_lt_i32_e64 s[18:19], v58, v52
	v_lshlrev_b32_e32 v1, 4, v1
	v_add_u32_e32 v193, 0xf800, v192
	v_cndmask_b32_e64 v58, v249, v58, s[18:19]
	v_lshlrev_b32_e32 v199, 2, v58
	v_xor_b32_e32 v58, 32, v249
	v_cmp_lt_i32_e64 s[18:19], v58, v52
	s_mov_b32 s46, 0
	v_lshl_add_u32 v194, v182, 2, s62
	v_cndmask_b32_e64 v52, v249, v58, s[18:19]
	v_lshlrev_b32_e32 v200, 2, v52
	v_add_u32_e32 v201, 0, v54
	v_add_u32_e32 v202, 0, v2
	v_add_u32_e32 v203, 0, v3
	v_add_u32_e32 v204, 0, v53
	v_add_u32_e32 v205, 0, v55
	v_add_u32_e32 v206, 0, v56
	v_add_u32_e32 v207, 0, v57
	v_add_u32_e32 v208, 0, v1
	s_waitcnt vmcnt(0)
	s_branch .LBB0_284

; #define LAS __attribute__((address_space(3)))
; #define CONV_LOAD(uu) do { const int b_ = (uu) >> 8, t0_ = ((uu) & 255) * 32; _Pragma("unroll") for (int i = 0; i < 8; ++i) { const int idx = tid + i * 512, row = idx >> 6, c16 = idx & 63, tok = t0_ - 15 + row; \
;         pf[i] = (v4u){0u, 0u, 0u, 0u}; if (idx < 62 * 64 && tok >= 0 && tok < SEQ) pf[i] = *(const v4u*)(CG + ((size_t)(b_ * SEQ + tok) * CW + c16 * 8)); } } while (0)
; __device__ __forceinline__ void conv_phase(const Frame& F, const bf16* CG, bf16* CAT, const float* dw_w, const float* dw_b, const float* ln_g, const float* ln_b) {
;     ...
;     const int ub = (F.vcu >> 5) * 256 + (F.vcu & 31);
;     CONV_LOAD(ub);
;     for (int kk = 0; kk < 8; ++kk) { const int u = ub + 32 * kk;
;         const int b = u >> 8, t0 = (u & 255) * 32;
; #pragma unroll
;         for (int i = 0; i < 8; ++i) { const int idx = tid + i * 512; if (idx < 62 * 64) *(LAS v4u*)(it + idx * 4) = pf[i]; }
;         __syncthreads();
;         if (kk + 1 < 8) CONV_LOAD(u + 32);
.LBB0_292:
	s_waitcnt vmcnt(4)
	ds_write_b128 v208, v[48:51]
.LBB0_293:
	s_or_b64 exec, exec, s[18:19]
	s_add_i32 s33, s88, s46
	s_cmpk_eq_i32 s46, 0x1c00
	s_waitcnt vmcnt(4) lgkmcnt(0)
	s_barrier
	s_cbranch_scc1 .LBB0_283
	s_add_i32 s18, s33, 0x400
	s_and_b32 s48, s18, 0x1fe0
	s_add_i32 s48, s48, -15
	v_add_u32_e32 v1, s48, v182
	v_mov_b32_e32 v22, v0
	v_mov_b32_e32 v23, v0
	s_and_b32 s47, s18, 0xffffe000
	v_cmp_gt_u32_e64 s[18:19], s34, v1
	v_mov_b32_e32 v20, v0
	v_mov_b32_e32 v21, v0
	v_mov_b64_e32 v[26:27], v[22:23]
	s_and_b64 s[58:59], vcc, s[18:19]
	v_mov_b64_e32 v[24:25], v[20:21]
	s_and_saveexec_b64 s[18:19], s[58:59]
	s_cbranch_execz .LBB0_296
	v_or_b32_e32 v2, s47, v1
	v_ashrrev_i32_e32 v3, 31, v2
	v_lshlrev_b64 v[2:3], 10, v[2:3]
	v_lshl_add_u64 v[2:3], v[148:149], 0, v[2:3]
	global_load_dwordx4 v[24:27], v[2:3], off

; #define LAS __attribute__((address_space(3)))
; __device__ __forceinline__ void conv_phase(const Frame& F, const bf16* CG, bf16* CAT, const float* dw_w, const float* dw_b, const float* ln_g, const float* ln_b) {
;     ...
;         for (int i = 0; i < 8; ++i) { const int idx = tid + i * 512; if (idx < 62 * 64) *(LAS v4u*)(it + idx * 4) = pf[i]; }
.LBB0_310:
	s_waitcnt vmcnt(4)
	ds_write_b128 v201, v[24:27]
	s_or_b64 exec, exec, s[18:19]
	s_and_saveexec_b64 s[18:19], s[0:1]
	s_cbranch_execz .LBB0_286
.LBB0_311:
	s_waitcnt vmcnt(4)
	ds_write_b128 v202, v[20:23]
	s_or_b64 exec, exec, s[18:19]
	s_and_saveexec_b64 s[18:19], s[16:17]
	s_cbranch_execz .LBB0_287
.LBB0_312:
	s_waitcnt vmcnt(4)
	ds_write_b128 v203, v[28:31]
	s_or_b64 exec, exec, s[18:19]
	s_and_saveexec_b64 s[18:19], s[4:5]
	s_cbranch_execz .LBB0_288
.LBB0_313:
	s_waitcnt vmcnt(4)
	ds_write_b128 v204, v[32:35]
	s_or_b64 exec, exec, s[18:19]
	s_and_saveexec_b64 s[18:19], s[6:7]
	s_cbranch_execz .LBB0_289
.LBB0_314:
	s_waitcnt vmcnt(4)
	ds_write_b128 v205, v[36:39]
	s_or_b64 exec, exec, s[18:19]
	s_and_saveexec_b64 s[18:19], s[10:11]
	s_cbranch_execz .LBB0_290
.LBB0_315:
	s_waitcnt vmcnt(4)
	ds_write_b128 v206, v[40:43]
	s_or_b64 exec, exec, s[18:19]
	s_and_saveexec_b64 s[18:19], s[12:13]
	s_cbranch_execz .LBB0_291
.LBB0_316:
	s_waitcnt vmcnt(4)
	ds_write_b128 v207, v[44:47]
	s_or_b64 exec, exec, s[18:19]
	s_and_saveexec_b64 s[18:19], s[14:15]
	s_cbranch_execnz .LBB0_292
	s_branch .LBB0_293
